# hoisted lane constants + vmcnt(1) + coalesced waits, re-padded to the baseline's code placement after the scan phase
# baseline (speedup 1.0000x reference)
.Lmy_ck_drE_h:
	s_waitcnt lgkmcnt(0)
	s_bfe_u32 s96, s62, 0x20006
	s_and_b32 s97, s96, 1
	s_mul_i32 s97, s97, 0x2700
	s_mov_b32 s101, 0x1c000
	s_mov_b32 s100, 0x6100
	s_bitcmp0_b32 s65, 0
	s_cselect_b32 s101, 0xe000, s101
	s_cselect_b32 s100, 0x4e00, s100
	s_cmp_gt_u32 s96, 1
	s_cselect_b32 s100, s100, 0
	s_add_i32 s97, s97, s101
	s_add_i32 s97, s97, s100
	s_mov_b32 s96, s97
	v_and_b32_e32 v72, 3, v233
	v_lshrrev_b32_e32 v73, 2, v233
	v_lshlrev_b32_e32 v72, 2, v72
	v_lshl_add_u32 v72, v73, 8, v72
	v_lshl_add_u32 v72, v234, 6, v72
	s_add_i32 s97, s96, 0x1000
	v_add_u32_e32 v78, s97, v72
	v_xor_b32_e32 v79, v224, v234
	v_lshl_add_u32 v79, v79, 4, s96
	ds_read_b128 v[96:99], v79
	ds_read_b128 v[100:103], v79 offset:1024
	ds_read_b128 v[104:107], v79 offset:2048
	ds_read_b128 v[108:111], v79 offset:3072
	ds_read_b32 v80, v78
	ds_read_b32 v81, v78 offset:16
	ds_read_b32 v82, v78 offset:32
	ds_read_b32 v83, v78 offset:48
	ds_read_b32 v84, v78 offset:1024
	ds_read_b32 v85, v78 offset:1040
	ds_read_b32 v86, v78 offset:1056
	ds_read_b32 v87, v78 offset:1072
	ds_read_b32 v88, v78 offset:2048
	ds_read_b32 v89, v78 offset:2064
	ds_read_b32 v90, v78 offset:2080
	ds_read_b32 v91, v78 offset:2096
	ds_read_b32 v92, v78 offset:3072
	ds_read_b32 v93, v78 offset:3088
	ds_read_b32 v94, v78 offset:3104
	ds_read_b32 v95, v78 offset:3120
	v_lshl_add_u32 v74, v224, 2, s96
	ds_write_b32 v74, v235 offset:9728
	v_add_u32_e32 v75, -1, v233
	v_mov_b32_e32 v76, -1
	v_cndmask_b32_e64 v75, v76, v75, s[98:99]
	v_cmp_lt_u32_e64 s[100:101], 7, v233
	v_add_u32_e32 v76, -8, v233
	v_and_b32_e32 v77, 1, v234
	v_cndmask_b32_e64 v75, v75, v76, s[100:101]
	v_lshlrev_b32_e32 v77, 2, v77
	v_sub_u32_e32 v76, v75, v77
	v_lshlrev_b32_e32 v77, 2, v234
	v_sub_u32_e32 v77, v233, v77
	v_add_u32_e32 v77, -1, v77
	s_waitcnt lgkmcnt(10)
	v_mfma_f32_16x16x4_f32 v[244:247], v80, v96, 0
	v_mfma_f32_16x16x4_f32 v[240:243], v81, v97, 0
	v_mfma_f32_16x16x4_f32 v[244:247], v82, v98, v[244:247]
	v_mfma_f32_16x16x4_f32 v[240:243], v83, v99, v[240:243]
	v_mfma_f32_16x16x4_f32 v[244:247], v84, v100, v[244:247]
	v_mfma_f32_16x16x4_f32 v[240:243], v85, v101, v[240:243]
	v_mfma_f32_16x16x4_f32 v[244:247], v86, v102, v[244:247]
	s_waitcnt lgkmcnt(2)
	v_mfma_f32_16x16x4_f32 v[240:243], v87, v103, v[240:243]
	v_mfma_f32_16x16x4_f32 v[244:247], v88, v104, v[244:247]
	v_mfma_f32_16x16x4_f32 v[240:243], v89, v105, v[240:243]
	v_mfma_f32_16x16x4_f32 v[244:247], v90, v106, v[244:247]
	v_mfma_f32_16x16x4_f32 v[240:243], v91, v107, v[240:243]
	v_mfma_f32_16x16x4_f32 v[244:247], v92, v108, v[244:247]
	v_mfma_f32_16x16x4_f32 v[240:243], v93, v109, v[240:243]
	v_mfma_f32_16x16x4_f32 v[244:247], v94, v110, v[244:247]
	s_waitcnt lgkmcnt(1)
	v_mfma_f32_16x16x4_f32 v[240:243], v95, v111, v[240:243]
	s_nop 9
	v_add_f32_e32 v244, v244, v240
	v_add_f32_e32 v245, v245, v241
	v_add_f32_e32 v246, v246, v242
	v_add_f32_e32 v247, v247, v243
	v_cmp_le_i32_e64 s[96:97], 0, v76
	v_cmp_le_i32_e64 s[100:101], 1, v76
	s_nop 0
	v_cndmask_b32_e64 v128, 0, v244, s[96:97]
	v_cndmask_b32_e64 v129, 0, v245, s[100:101]
	v_cmp_le_i32_e64 s[96:97], 2, v76
	v_cmp_le_i32_e64 s[100:101], 3, v76
	s_nop 0
	v_cndmask_b32_e64 v130, 0, v246, s[96:97]
	v_cndmask_b32_e64 v131, 0, v247, s[100:101]
	s_bfe_u32 s96, s62, 0x20006
	s_and_b32 s97, s96, 1
	s_mul_i32 s97, s97, 0x2700
	s_mov_b32 s101, 0x1c000
	s_mov_b32 s100, 0x6100
	s_bitcmp0_b32 s65, 0
	s_cselect_b32 s101, 0xe000, s101
	s_cselect_b32 s100, 0x4e00, s100
	s_cmp_gt_u32 s96, 1
	s_cselect_b32 s100, s100, 0
	s_add_i32 s97, s97, s101
	s_add_i32 s97, s97, s100
	v_xor_b32_e32 v74, v224, v234
	v_lshl_add_u32 v74, v74, 4, s97
	ds_write_b128 v74, v[128:131] offset:8448
	v_lshlrev_b32_e32 v75, 7, v234
	v_lshl_add_u32 v75, v233, 2, v75
	v_add_u32_e32 v75, s97, v75
	v_cmp_le_i32_e64 s[96:97], 0, v77
	v_cmp_le_i32_e64 s[100:101], 1, v77
	s_nop 0
	v_cndmask_b32_e64 v132, 0, v244, s[96:97]
	v_cndmask_b32_e64 v133, 0, v245, s[100:101]
	v_cmp_le_i32_e64 s[96:97], 2, v77
	v_cmp_le_i32_e64 s[100:101], 3, v77
	s_nop 0
	v_cndmask_b32_e64 v134, 0, v246, s[96:97]
	v_cndmask_b32_e64 v135, 0, v247, s[100:101]
	s_mov_b64 exec, 0x00ff00ff
	ds_write_b32 v75, v132 offset:9472
	ds_write_b32 v75, v133 offset:9504
	ds_write_b32 v75, v134 offset:9536
	ds_write_b32 v75, v135 offset:9568
	s_mov_b64 exec, -1
	s_branch .LBB0_655
	s_nop 0
	s_nop 0
	s_nop 0
	s_nop 0
	s_nop 0
	s_nop 0
	s_nop 0
	s_nop 0
	s_nop 0
	s_nop 0
	s_nop 0
	s_nop 0
	s_nop 0
	s_nop 0
	s_nop 0
